# MO8 + TRIM: no non-MFMA instructions between the barriers of the MFMA segments (setprio moved outside the barriers, redundant lgkmcnt(0) and mid setprio pair dropped)
# speedup vs baseline: 1.0231x; 1.0231x over previous
.LBB0_139:
	s_add_u32 s22, s18, 0xfff00080
	s_addc_u32 s23, s19, -1
	s_add_i32 s49, 0, 0x10000
	s_cmp_eq_u32 s48, 60
	s_cselect_b32 s25, s9, s23
	s_cselect_b32 s24, s44, s22
	s_cselect_b32 s23, s7, s47
	s_cselect_b32 s22, s45, s46
	s_add_i32 s52, 0, 0x14000
	v_add_u32_e32 v156, s49, v145
	v_add_u32_e32 v172, s52, v145
	ds_read_b128 v[140:143], v156
	ds_read_b128 v[148:151], v156 offset:1024
	ds_read_b128 v[152:155], v156 offset:2048
	ds_read_b128 v[156:159], v156 offset:3072
	ds_read_b128 v[160:163], v172
	ds_read_b128 v[164:167], v172 offset:1024
	ds_read_b128 v[168:171], v172 offset:2048
	ds_read_b128 v[190:193], v172 offset:3072
	v_lshl_add_u64 v[172:173], s[18:19], 0, v[136:137]
	s_add_i32 m0, s31, 0xc000
	ds_read_b128 v[194:197], v147
	ds_read_b128 v[198:201], v147 offset:1024
	ds_read_b128 v[202:205], v147 offset:2048
	ds_read_b128 v[206:209], v147 offset:3072
	ds_read_b128 v[228:231], v147 offset:4096
	ds_read_b128 v[232:235], v147 offset:5120
	ds_read_b128 v[236:239], v147 offset:6144
	ds_read_b128 v[240:243], v147 offset:7168
	global_load_lds_dwordx4 v[172:173], off
	v_lshl_add_u64 v[172:173], s[18:19], 0, v[138:139]
	s_add_i32 m0, s31, 0xe000
	s_nop 0
	global_load_lds_dwordx4 v[172:173], off
	s_waitcnt vmcnt(8)
	s_waitcnt lgkmcnt(0)
	s_setprio 1
	s_barrier
	v_mfma_f32_16x16x32_bf16 v[126:129], v[140:143], v[194:197], v[126:129]
	v_mfma_f32_16x16x32_bf16 v[126:129], v[148:151], v[198:201], v[126:129]
	v_mfma_f32_16x16x32_bf16 v[118:121], v[148:151], v[206:209], v[118:121]
	v_mfma_f32_16x16x32_bf16 v[118:121], v[140:143], v[202:205], v[118:121]
	v_mfma_f32_16x16x32_bf16 v[102:105], v[140:143], v[228:231], v[102:105]
	v_mfma_f32_16x16x32_bf16 v[102:105], v[148:151], v[232:235], v[102:105]
	v_mfma_f32_16x16x32_bf16 v[86:89], v[148:151], v[240:243], v[86:89]
	v_mfma_f32_16x16x32_bf16 v[86:89], v[140:143], v[236:239], v[86:89]
	v_mfma_f32_16x16x32_bf16 v[78:81], v[152:155], v[236:239], v[78:81]
	v_mfma_f32_16x16x32_bf16 v[78:81], v[156:159], v[240:243], v[78:81]
	v_mfma_f32_16x16x32_bf16 v[94:97], v[156:159], v[232:235], v[94:97]
	v_mfma_f32_16x16x32_bf16 v[94:97], v[152:155], v[228:231], v[94:97]
	v_mfma_f32_16x16x32_bf16 v[110:113], v[152:155], v[202:205], v[110:113]
	v_mfma_f32_16x16x32_bf16 v[110:113], v[156:159], v[206:209], v[110:113]
	v_mfma_f32_16x16x32_bf16 v[122:125], v[156:159], v[198:201], v[122:125]
	v_mfma_f32_16x16x32_bf16 v[122:125], v[152:155], v[194:197], v[122:125]
	v_mfma_f32_16x16x32_bf16 v[114:117], v[160:163], v[194:197], v[114:117]
	v_mfma_f32_16x16x32_bf16 v[114:117], v[164:167], v[198:201], v[114:117]
	v_mfma_f32_16x16x32_bf16 v[98:101], v[164:167], v[206:209], v[98:101]
	v_mfma_f32_16x16x32_bf16 v[98:101], v[160:163], v[202:205], v[98:101]
	v_mfma_f32_16x16x32_bf16 v[82:85], v[160:163], v[228:231], v[82:85]
	v_mfma_f32_16x16x32_bf16 v[82:85], v[164:167], v[232:235], v[82:85]
	v_mfma_f32_16x16x32_bf16 v[70:73], v[164:167], v[240:243], v[70:73]
	v_mfma_f32_16x16x32_bf16 v[70:73], v[160:163], v[236:239], v[70:73]
	v_mfma_f32_16x16x32_bf16 v[66:69], v[168:171], v[236:239], v[66:69]
	v_mfma_f32_16x16x32_bf16 v[66:69], v[190:193], v[240:243], v[66:69]
	v_mfma_f32_16x16x32_bf16 v[74:77], v[190:193], v[232:235], v[74:77]
	v_mfma_f32_16x16x32_bf16 v[74:77], v[168:171], v[228:231], v[74:77]
	v_mfma_f32_16x16x32_bf16 v[90:93], v[168:171], v[202:205], v[90:93]
	v_mfma_f32_16x16x32_bf16 v[90:93], v[190:193], v[206:209], v[90:93]
	v_mfma_f32_16x16x32_bf16 v[106:109], v[190:193], v[198:201], v[106:109]
	v_mfma_f32_16x16x32_bf16 v[106:109], v[168:171], v[194:197], v[106:109]
	s_barrier
	s_setprio 0
	s_add_i32 s49, s49, s26
	v_lshl_add_u64 v[172:173], s[22:23], 0, v[0:1]
	s_mov_b32 m0, s49
	ds_read_b128 v[194:197], v147 offset:16384
	ds_read_b128 v[198:201], v147 offset:17408
	ds_read_b128 v[202:205], v147 offset:18432
	ds_read_b128 v[206:209], v147 offset:19456
	ds_read_b128 v[228:231], v147 offset:20480
	ds_read_b128 v[232:235], v147 offset:21504
	ds_read_b128 v[236:239], v147 offset:22528
	ds_read_b128 v[240:243], v147 offset:23552
	global_load_lds_dwordx4 v[172:173], off
	s_add_i32 m0, s49, 0x2000
	s_add_u32 s50, s22, 0x100000
	v_lshl_add_u64 v[178:179], s[22:23], 0, v[130:131]
	s_addc_u32 s51, s23, 0
	s_add_i32 s49, s52, s26
	global_load_lds_dwordx4 v[178:179], off
	v_lshl_add_u64 v[180:181], s[50:51], 0, v[0:1]
	s_mov_b32 m0, s49
	v_lshl_add_u64 v[210:211], s[24:25], 0, v[132:133]
	global_load_lds_dwordx4 v[180:181], off
	v_lshl_add_u64 v[180:181], s[50:51], 0, v[130:131]
	s_add_i32 m0, s49, 0x2000
	s_nop 0
	global_load_lds_dwordx4 v[180:181], off
	v_lshl_add_u64 v[180:181], s[24:25], 0, v[134:135]
	s_mov_b32 m0, s31
	s_nop 0
	global_load_lds_dwordx4 v[180:181], off
	s_mov_b32 m0, s36
	s_nop 0
	global_load_lds_dwordx4 v[210:211], off
	s_waitcnt vmcnt(8)
	s_waitcnt lgkmcnt(0)
	s_setprio 1
	s_barrier
	v_mfma_f32_16x16x32_bf16 v[62:65], v[140:143], v[194:197], v[62:65]
	v_mfma_f32_16x16x32_bf16 v[62:65], v[148:151], v[198:201], v[62:65]
	v_mfma_f32_16x16x32_bf16 v[54:57], v[148:151], v[206:209], v[54:57]
	v_mfma_f32_16x16x32_bf16 v[54:57], v[140:143], v[202:205], v[54:57]
	v_mfma_f32_16x16x32_bf16 v[38:41], v[140:143], v[228:231], v[38:41]
	v_mfma_f32_16x16x32_bf16 v[38:41], v[148:151], v[232:235], v[38:41]
	v_mfma_f32_16x16x32_bf16 v[22:25], v[148:151], v[240:243], v[22:25]
	v_mfma_f32_16x16x32_bf16 v[22:25], v[140:143], v[236:239], v[22:25]
	v_mfma_f32_16x16x32_bf16 v[14:17], v[152:155], v[236:239], v[14:17]
	v_mfma_f32_16x16x32_bf16 v[14:17], v[156:159], v[240:243], v[14:17]
	v_mfma_f32_16x16x32_bf16 v[30:33], v[156:159], v[232:235], v[30:33]
	v_mfma_f32_16x16x32_bf16 v[30:33], v[152:155], v[228:231], v[30:33]
	v_mfma_f32_16x16x32_bf16 v[46:49], v[152:155], v[202:205], v[46:49]
	v_mfma_f32_16x16x32_bf16 v[46:49], v[156:159], v[206:209], v[46:49]
	v_mfma_f32_16x16x32_bf16 v[58:61], v[156:159], v[198:201], v[58:61]
	v_mfma_f32_16x16x32_bf16 v[58:61], v[152:155], v[194:197], v[58:61]
	v_mfma_f32_16x16x32_bf16 v[50:53], v[160:163], v[194:197], v[50:53]
	v_mfma_f32_16x16x32_bf16 v[50:53], v[164:167], v[198:201], v[50:53]
	v_mfma_f32_16x16x32_bf16 v[34:37], v[164:167], v[206:209], v[34:37]
	v_mfma_f32_16x16x32_bf16 v[34:37], v[160:163], v[202:205], v[34:37]
	v_mfma_f32_16x16x32_bf16 v[18:21], v[160:163], v[228:231], v[18:21]
	v_mfma_f32_16x16x32_bf16 v[18:21], v[164:167], v[232:235], v[18:21]
	v_mfma_f32_16x16x32_bf16 v[6:9], v[164:167], v[240:243], v[6:9]
	v_mfma_f32_16x16x32_bf16 v[6:9], v[160:163], v[236:239], v[6:9]
	v_mfma_f32_16x16x32_bf16 v[2:5], v[168:171], v[236:239], v[2:5]
	v_mfma_f32_16x16x32_bf16 v[2:5], v[190:193], v[240:243], v[2:5]
	v_mfma_f32_16x16x32_bf16 v[10:13], v[190:193], v[232:235], v[10:13]
	v_mfma_f32_16x16x32_bf16 v[10:13], v[168:171], v[228:231], v[10:13]
	v_mfma_f32_16x16x32_bf16 v[26:29], v[168:171], v[202:205], v[26:29]
	v_mfma_f32_16x16x32_bf16 v[26:29], v[190:193], v[206:209], v[26:29]
	v_mfma_f32_16x16x32_bf16 v[42:45], v[190:193], v[198:201], v[42:45]
	v_mfma_f32_16x16x32_bf16 v[42:45], v[168:171], v[194:197], v[42:45]
	s_barrier
	s_setprio 0
	s_add_i32 s49, 0, 0x18000
	s_add_i32 s50, 0, 0x1c000
	v_add_u32_e32 v156, s49, v145
	v_add_u32_e32 v175, s50, v145
	ds_read_b128 v[140:143], v156
	ds_read_b128 v[148:151], v156 offset:1024
	ds_read_b128 v[152:155], v156 offset:2048
	ds_read_b128 v[156:159], v156 offset:3072
	ds_read_b128 v[160:163], v175
	ds_read_b128 v[164:167], v175 offset:1024
	ds_read_b128 v[168:171], v175 offset:2048
	ds_read_b128 v[190:193], v175 offset:3072
	s_add_u32 s24, s24, 0x100000
	s_addc_u32 s25, s25, 0
	s_mov_b32 m0, s37
	v_lshl_add_u64 v[244:245], s[24:25], 0, v[134:135]
	ds_read_b128 v[194:197], v147 offset:32768
	ds_read_b128 v[198:201], v147 offset:33792
	ds_read_b128 v[202:205], v147 offset:34816
	ds_read_b128 v[206:209], v147 offset:35840
	ds_read_b128 v[228:231], v147 offset:36864
	ds_read_b128 v[232:235], v147 offset:37888
	ds_read_b128 v[236:239], v147 offset:38912
	ds_read_b128 v[240:243], v147 offset:39936
	global_load_lds_dwordx4 v[244:245], off
	v_lshl_add_u64 v[244:245], s[24:25], 0, v[132:133]
	s_mov_b32 m0, s38
	s_nop 0
	global_load_lds_dwordx4 v[244:245], off
	s_waitcnt vmcnt(8)
	s_waitcnt lgkmcnt(0)
	s_setprio 1
	s_barrier
	v_mfma_f32_16x16x32_bf16 v[126:129], v[140:143], v[194:197], v[126:129]
	v_mfma_f32_16x16x32_bf16 v[126:129], v[148:151], v[198:201], v[126:129]
	v_mfma_f32_16x16x32_bf16 v[118:121], v[148:151], v[206:209], v[118:121]
	v_mfma_f32_16x16x32_bf16 v[118:121], v[140:143], v[202:205], v[118:121]
	v_mfma_f32_16x16x32_bf16 v[102:105], v[140:143], v[228:231], v[102:105]
	v_mfma_f32_16x16x32_bf16 v[102:105], v[148:151], v[232:235], v[102:105]
	v_mfma_f32_16x16x32_bf16 v[86:89], v[148:151], v[240:243], v[86:89]
	v_mfma_f32_16x16x32_bf16 v[86:89], v[140:143], v[236:239], v[86:89]
	v_mfma_f32_16x16x32_bf16 v[78:81], v[152:155], v[236:239], v[78:81]
	v_mfma_f32_16x16x32_bf16 v[78:81], v[156:159], v[240:243], v[78:81]
	v_mfma_f32_16x16x32_bf16 v[94:97], v[156:159], v[232:235], v[94:97]
	v_mfma_f32_16x16x32_bf16 v[94:97], v[152:155], v[228:231], v[94:97]
	v_mfma_f32_16x16x32_bf16 v[110:113], v[152:155], v[202:205], v[110:113]
	v_mfma_f32_16x16x32_bf16 v[110:113], v[156:159], v[206:209], v[110:113]
	v_mfma_f32_16x16x32_bf16 v[122:125], v[156:159], v[198:201], v[122:125]
	v_mfma_f32_16x16x32_bf16 v[122:125], v[152:155], v[194:197], v[122:125]
	v_mfma_f32_16x16x32_bf16 v[114:117], v[160:163], v[194:197], v[114:117]
	v_mfma_f32_16x16x32_bf16 v[114:117], v[164:167], v[198:201], v[114:117]
	v_mfma_f32_16x16x32_bf16 v[98:101], v[164:167], v[206:209], v[98:101]
	v_mfma_f32_16x16x32_bf16 v[98:101], v[160:163], v[202:205], v[98:101]
	v_mfma_f32_16x16x32_bf16 v[82:85], v[160:163], v[228:231], v[82:85]
	v_mfma_f32_16x16x32_bf16 v[82:85], v[164:167], v[232:235], v[82:85]
	v_mfma_f32_16x16x32_bf16 v[70:73], v[164:167], v[240:243], v[70:73]
	v_mfma_f32_16x16x32_bf16 v[70:73], v[160:163], v[236:239], v[70:73]
	v_mfma_f32_16x16x32_bf16 v[66:69], v[168:171], v[236:239], v[66:69]
	v_mfma_f32_16x16x32_bf16 v[66:69], v[190:193], v[240:243], v[66:69]
	v_mfma_f32_16x16x32_bf16 v[74:77], v[190:193], v[232:235], v[74:77]
	v_mfma_f32_16x16x32_bf16 v[74:77], v[168:171], v[228:231], v[74:77]
	v_mfma_f32_16x16x32_bf16 v[90:93], v[168:171], v[202:205], v[90:93]
	v_mfma_f32_16x16x32_bf16 v[90:93], v[190:193], v[206:209], v[90:93]
	v_mfma_f32_16x16x32_bf16 v[106:109], v[190:193], v[198:201], v[106:109]
	v_mfma_f32_16x16x32_bf16 v[106:109], v[168:171], v[194:197], v[106:109]
	s_barrier
	s_setprio 0
	s_add_i32 s24, s49, s26
	v_lshl_add_u64 v[172:173], v[172:173], 0, s[34:35]
	s_mov_b32 m0, s24
	ds_read_b128 v[194:197], v147 offset:49152
	ds_read_b128 v[198:201], v147 offset:50176
	ds_read_b128 v[202:205], v147 offset:51200
	ds_read_b128 v[206:209], v147 offset:52224
	ds_read_b128 v[228:231], v147 offset:53248
	ds_read_b128 v[232:235], v147 offset:54272
	ds_read_b128 v[236:239], v147 offset:55296
	ds_read_b128 v[240:243], v147 offset:56320
	global_load_lds_dwordx4 v[172:173], off
	s_add_i32 m0, s24, 0x2000
	s_add_u32 s22, s22, 0x100080
	v_lshl_add_u64 v[172:173], v[178:179], 0, s[34:35]
	s_addc_u32 s23, s23, 0
	s_add_i32 s24, s50, s26
	global_load_lds_dwordx4 v[172:173], off
	v_lshl_add_u64 v[172:173], s[22:23], 0, v[0:1]
	s_mov_b32 m0, s24
	s_nop 0
	global_load_lds_dwordx4 v[172:173], off
	v_lshl_add_u64 v[172:173], s[22:23], 0, v[130:131]
	s_add_i32 m0, s24, 0x2000
	s_nop 0
	global_load_lds_dwordx4 v[172:173], off
	v_lshl_add_u64 v[172:173], v[180:181], 0, s[34:35]
	s_mov_b32 m0, s39
	s_nop 0
	global_load_lds_dwordx4 v[172:173], off
	v_lshl_add_u64 v[172:173], v[210:211], 0, s[34:35]
	s_mov_b32 m0, s40
	s_nop 0
	global_load_lds_dwordx4 v[172:173], off
	s_waitcnt vmcnt(8)
	s_waitcnt lgkmcnt(0)
	s_setprio 1
	s_barrier
	v_mfma_f32_16x16x32_bf16 v[62:65], v[140:143], v[194:197], v[62:65]
	v_mfma_f32_16x16x32_bf16 v[62:65], v[148:151], v[198:201], v[62:65]
	v_mfma_f32_16x16x32_bf16 v[54:57], v[148:151], v[206:209], v[54:57]
	v_mfma_f32_16x16x32_bf16 v[54:57], v[140:143], v[202:205], v[54:57]
	v_mfma_f32_16x16x32_bf16 v[38:41], v[140:143], v[228:231], v[38:41]
	v_mfma_f32_16x16x32_bf16 v[38:41], v[148:151], v[232:235], v[38:41]
	v_mfma_f32_16x16x32_bf16 v[22:25], v[148:151], v[240:243], v[22:25]
	v_mfma_f32_16x16x32_bf16 v[22:25], v[140:143], v[236:239], v[22:25]
	v_mfma_f32_16x16x32_bf16 v[14:17], v[152:155], v[236:239], v[14:17]
	v_mfma_f32_16x16x32_bf16 v[14:17], v[156:159], v[240:243], v[14:17]
	v_mfma_f32_16x16x32_bf16 v[30:33], v[156:159], v[232:235], v[30:33]
	v_mfma_f32_16x16x32_bf16 v[30:33], v[152:155], v[228:231], v[30:33]
	v_mfma_f32_16x16x32_bf16 v[46:49], v[152:155], v[202:205], v[46:49]
	v_mfma_f32_16x16x32_bf16 v[46:49], v[156:159], v[206:209], v[46:49]
	v_mfma_f32_16x16x32_bf16 v[58:61], v[156:159], v[198:201], v[58:61]
	v_mfma_f32_16x16x32_bf16 v[58:61], v[152:155], v[194:197], v[58:61]
	v_mfma_f32_16x16x32_bf16 v[50:53], v[160:163], v[194:197], v[50:53]
	v_mfma_f32_16x16x32_bf16 v[50:53], v[164:167], v[198:201], v[50:53]
	v_mfma_f32_16x16x32_bf16 v[34:37], v[164:167], v[206:209], v[34:37]
	v_mfma_f32_16x16x32_bf16 v[34:37], v[160:163], v[202:205], v[34:37]
	v_mfma_f32_16x16x32_bf16 v[18:21], v[160:163], v[228:231], v[18:21]
	v_mfma_f32_16x16x32_bf16 v[18:21], v[164:167], v[232:235], v[18:21]
	v_mfma_f32_16x16x32_bf16 v[6:9], v[164:167], v[240:243], v[6:9]
	v_mfma_f32_16x16x32_bf16 v[6:9], v[160:163], v[236:239], v[6:9]
	v_mfma_f32_16x16x32_bf16 v[2:5], v[168:171], v[236:239], v[2:5]
	v_mfma_f32_16x16x32_bf16 v[2:5], v[190:193], v[240:243], v[2:5]
	v_mfma_f32_16x16x32_bf16 v[10:13], v[190:193], v[232:235], v[10:13]
	v_mfma_f32_16x16x32_bf16 v[10:13], v[168:171], v[228:231], v[10:13]
	v_mfma_f32_16x16x32_bf16 v[26:29], v[168:171], v[202:205], v[26:29]
	v_mfma_f32_16x16x32_bf16 v[26:29], v[190:193], v[206:209], v[26:29]
	v_mfma_f32_16x16x32_bf16 v[42:45], v[190:193], v[198:201], v[42:45]
	v_mfma_f32_16x16x32_bf16 v[42:45], v[168:171], v[194:197], v[42:45]
	s_barrier
	s_setprio 0
	s_add_i32 s48, s48, 2
	s_add_u32 s18, s18, 0x100
	s_addc_u32 s19, s19, 0
	s_add_u32 s46, s46, 0x100
	s_addc_u32 s47, s47, 0
	s_cmp_gt_u32 s48, 61
	s_cbranch_scc0 .LBB0_139
	s_and_b64 vcc, exec, s[4:5]
	s_cbranch_vccz .LBB0_142
	s_barrier

.LBB0_575:
	s_add_u32 s22, s18, 0xfff00080
	s_addc_u32 s23, s19, -1
	s_add_i32 s53, 0, 0x10000
	s_cmp_eq_u32 s52, 60
	s_cselect_b32 s25, s9, s23
	s_cselect_b32 s24, s48, s22
	v_add_u32_e32 v140, s53, v143
	s_cselect_b32 s23, s7, s51
	s_cselect_b32 s22, s49, s50
	s_add_i32 s56, 0, 0x14000
	ds_read_b128 v[146:149], v140
	ds_read_b128 v[150:153], v140 offset:1024
	ds_read_b128 v[154:157], v140 offset:2048
	ds_read_b128 v[158:161], v140 offset:3072
	v_add_u32_e32 v140, s56, v143
	ds_read_b128 v[162:165], v140
	ds_read_b128 v[166:169], v140 offset:1024
	ds_read_b128 v[170:173], v140 offset:2048
	ds_read_b128 v[178:181], v140 offset:3072
	v_lshl_add_u64 v[140:141], s[18:19], 0, v[136:137]
	s_add_i32 m0, s39, 0xc000
	ds_read_b128 v[190:193], v145
	ds_read_b128 v[194:197], v145 offset:1024
	ds_read_b128 v[198:201], v145 offset:2048
	ds_read_b128 v[202:205], v145 offset:3072
	ds_read_b128 v[206:209], v145 offset:4096
	ds_read_b128 v[228:231], v145 offset:5120
	ds_read_b128 v[232:235], v145 offset:6144
	ds_read_b128 v[236:239], v145 offset:7168
	global_load_lds_dwordx4 v[140:141], off
	v_lshl_add_u64 v[140:141], s[18:19], 0, v[138:139]
	s_add_i32 m0, s39, 0xe000
	s_nop 0
	global_load_lds_dwordx4 v[140:141], off
	s_waitcnt vmcnt(8)
	s_waitcnt lgkmcnt(0)
	s_setprio 1
	s_barrier
	v_mfma_f32_16x16x32_bf16 v[126:129], v[146:149], v[190:193], v[126:129]
	v_mfma_f32_16x16x32_bf16 v[126:129], v[150:153], v[194:197], v[126:129]
	v_mfma_f32_16x16x32_bf16 v[118:121], v[150:153], v[202:205], v[118:121]
	v_mfma_f32_16x16x32_bf16 v[118:121], v[146:149], v[198:201], v[118:121]
	v_mfma_f32_16x16x32_bf16 v[102:105], v[146:149], v[206:209], v[102:105]
	v_mfma_f32_16x16x32_bf16 v[102:105], v[150:153], v[228:231], v[102:105]
	v_mfma_f32_16x16x32_bf16 v[86:89], v[150:153], v[236:239], v[86:89]
	v_mfma_f32_16x16x32_bf16 v[86:89], v[146:149], v[232:235], v[86:89]
	v_mfma_f32_16x16x32_bf16 v[78:81], v[154:157], v[232:235], v[78:81]
	v_mfma_f32_16x16x32_bf16 v[78:81], v[158:161], v[236:239], v[78:81]
	v_mfma_f32_16x16x32_bf16 v[94:97], v[158:161], v[228:231], v[94:97]
	v_mfma_f32_16x16x32_bf16 v[94:97], v[154:157], v[206:209], v[94:97]
	v_mfma_f32_16x16x32_bf16 v[110:113], v[154:157], v[198:201], v[110:113]
	v_mfma_f32_16x16x32_bf16 v[110:113], v[158:161], v[202:205], v[110:113]
	v_mfma_f32_16x16x32_bf16 v[122:125], v[158:161], v[194:197], v[122:125]
	v_mfma_f32_16x16x32_bf16 v[122:125], v[154:157], v[190:193], v[122:125]
	v_mfma_f32_16x16x32_bf16 v[114:117], v[162:165], v[190:193], v[114:117]
	v_mfma_f32_16x16x32_bf16 v[114:117], v[166:169], v[194:197], v[114:117]
	v_mfma_f32_16x16x32_bf16 v[98:101], v[166:169], v[202:205], v[98:101]
	v_mfma_f32_16x16x32_bf16 v[98:101], v[162:165], v[198:201], v[98:101]
	v_mfma_f32_16x16x32_bf16 v[82:85], v[162:165], v[206:209], v[82:85]
	v_mfma_f32_16x16x32_bf16 v[82:85], v[166:169], v[228:231], v[82:85]
	v_mfma_f32_16x16x32_bf16 v[70:73], v[166:169], v[236:239], v[70:73]
	v_mfma_f32_16x16x32_bf16 v[70:73], v[162:165], v[232:235], v[70:73]
	v_mfma_f32_16x16x32_bf16 v[66:69], v[170:173], v[232:235], v[66:69]
	v_mfma_f32_16x16x32_bf16 v[66:69], v[178:181], v[236:239], v[66:69]
	v_mfma_f32_16x16x32_bf16 v[74:77], v[178:181], v[228:231], v[74:77]
	v_mfma_f32_16x16x32_bf16 v[74:77], v[170:173], v[206:209], v[74:77]
	v_mfma_f32_16x16x32_bf16 v[90:93], v[170:173], v[198:201], v[90:93]
	v_mfma_f32_16x16x32_bf16 v[90:93], v[178:181], v[202:205], v[90:93]
	v_mfma_f32_16x16x32_bf16 v[106:109], v[178:181], v[194:197], v[106:109]
	v_mfma_f32_16x16x32_bf16 v[106:109], v[170:173], v[190:193], v[106:109]
	s_barrier
	s_setprio 0
	s_add_i32 s53, s53, s38
	v_lshl_add_u64 v[140:141], s[22:23], 0, v[0:1]
	s_mov_b32 m0, s53
	ds_read_b128 v[190:193], v145 offset:16384
	ds_read_b128 v[194:197], v145 offset:17408
	ds_read_b128 v[198:201], v145 offset:18432
	ds_read_b128 v[202:205], v145 offset:19456
	ds_read_b128 v[206:209], v145 offset:20480
	ds_read_b128 v[228:231], v145 offset:21504
	ds_read_b128 v[232:235], v145 offset:22528
	ds_read_b128 v[236:239], v145 offset:23552
	global_load_lds_dwordx4 v[140:141], off
	s_add_i32 m0, s53, 0x2000
	s_add_u32 s54, s22, 0x100000
	v_lshl_add_u64 v[186:187], s[22:23], 0, v[130:131]
	s_addc_u32 s55, s23, 0
	s_add_i32 s53, s56, s38
	global_load_lds_dwordx4 v[186:187], off
	v_lshl_add_u64 v[188:189], s[54:55], 0, v[0:1]
	s_mov_b32 m0, s53
	v_lshl_add_u64 v[210:211], s[24:25], 0, v[132:133]
	global_load_lds_dwordx4 v[188:189], off
	v_lshl_add_u64 v[188:189], s[54:55], 0, v[130:131]
	s_add_i32 m0, s53, 0x2000
	s_nop 0
	global_load_lds_dwordx4 v[188:189], off
	v_lshl_add_u64 v[188:189], s[24:25], 0, v[134:135]
	s_mov_b32 m0, s39
	s_nop 0
	global_load_lds_dwordx4 v[188:189], off
	s_mov_b32 m0, s40
	s_nop 0
	global_load_lds_dwordx4 v[210:211], off
	s_waitcnt vmcnt(8)
	s_waitcnt lgkmcnt(0)
	s_setprio 1
	s_barrier
	v_mfma_f32_16x16x32_bf16 v[62:65], v[146:149], v[190:193], v[62:65]
	v_mfma_f32_16x16x32_bf16 v[62:65], v[150:153], v[194:197], v[62:65]
	v_mfma_f32_16x16x32_bf16 v[54:57], v[150:153], v[202:205], v[54:57]
	v_mfma_f32_16x16x32_bf16 v[54:57], v[146:149], v[198:201], v[54:57]
	v_mfma_f32_16x16x32_bf16 v[38:41], v[146:149], v[206:209], v[38:41]
	v_mfma_f32_16x16x32_bf16 v[38:41], v[150:153], v[228:231], v[38:41]
	v_mfma_f32_16x16x32_bf16 v[22:25], v[150:153], v[236:239], v[22:25]
	v_mfma_f32_16x16x32_bf16 v[22:25], v[146:149], v[232:235], v[22:25]
	v_mfma_f32_16x16x32_bf16 v[14:17], v[154:157], v[232:235], v[14:17]
	v_mfma_f32_16x16x32_bf16 v[14:17], v[158:161], v[236:239], v[14:17]
	v_mfma_f32_16x16x32_bf16 v[30:33], v[158:161], v[228:231], v[30:33]
	v_mfma_f32_16x16x32_bf16 v[30:33], v[154:157], v[206:209], v[30:33]
	v_mfma_f32_16x16x32_bf16 v[46:49], v[154:157], v[198:201], v[46:49]
	v_mfma_f32_16x16x32_bf16 v[46:49], v[158:161], v[202:205], v[46:49]
	v_mfma_f32_16x16x32_bf16 v[58:61], v[158:161], v[194:197], v[58:61]
	v_mfma_f32_16x16x32_bf16 v[58:61], v[154:157], v[190:193], v[58:61]
	v_mfma_f32_16x16x32_bf16 v[50:53], v[162:165], v[190:193], v[50:53]
	v_mfma_f32_16x16x32_bf16 v[50:53], v[166:169], v[194:197], v[50:53]
	v_mfma_f32_16x16x32_bf16 v[34:37], v[166:169], v[202:205], v[34:37]
	v_mfma_f32_16x16x32_bf16 v[34:37], v[162:165], v[198:201], v[34:37]
	v_mfma_f32_16x16x32_bf16 v[18:21], v[162:165], v[206:209], v[18:21]
	v_mfma_f32_16x16x32_bf16 v[18:21], v[166:169], v[228:231], v[18:21]
	v_mfma_f32_16x16x32_bf16 v[6:9], v[166:169], v[236:239], v[6:9]
	v_mfma_f32_16x16x32_bf16 v[6:9], v[162:165], v[232:235], v[6:9]
	v_mfma_f32_16x16x32_bf16 v[2:5], v[170:173], v[232:235], v[2:5]
	v_mfma_f32_16x16x32_bf16 v[2:5], v[178:181], v[236:239], v[2:5]
	v_mfma_f32_16x16x32_bf16 v[10:13], v[178:181], v[228:231], v[10:13]
	v_mfma_f32_16x16x32_bf16 v[10:13], v[170:173], v[206:209], v[10:13]
	v_mfma_f32_16x16x32_bf16 v[26:29], v[170:173], v[198:201], v[26:29]
	v_mfma_f32_16x16x32_bf16 v[26:29], v[178:181], v[202:205], v[26:29]
	v_mfma_f32_16x16x32_bf16 v[42:45], v[178:181], v[194:197], v[42:45]
	v_mfma_f32_16x16x32_bf16 v[42:45], v[170:173], v[190:193], v[42:45]
	s_barrier
	s_setprio 0
	s_add_i32 s53, 0, 0x18000
	s_add_i32 s54, 0, 0x1c000
	v_add_u32_e32 v158, s53, v143
	v_add_u32_e32 v175, s54, v143
	ds_read_b128 v[146:149], v158
	ds_read_b128 v[150:153], v158 offset:1024
	ds_read_b128 v[154:157], v158 offset:2048
	ds_read_b128 v[158:161], v158 offset:3072
	ds_read_b128 v[162:165], v175
	ds_read_b128 v[166:169], v175 offset:1024
	ds_read_b128 v[170:173], v175 offset:2048
	ds_read_b128 v[178:181], v175 offset:3072
	s_add_u32 s24, s24, 0x100000
	s_addc_u32 s25, s25, 0
	s_mov_b32 m0, s41
	v_lshl_add_u64 v[226:227], s[24:25], 0, v[134:135]
	ds_read_b128 v[190:193], v145 offset:32768
	ds_read_b128 v[194:197], v145 offset:33792
	ds_read_b128 v[198:201], v145 offset:34816
	ds_read_b128 v[202:205], v145 offset:35840
	ds_read_b128 v[206:209], v145 offset:36864
	ds_read_b128 v[228:231], v145 offset:37888
	ds_read_b128 v[232:235], v145 offset:38912
	ds_read_b128 v[236:239], v145 offset:39936
	global_load_lds_dwordx4 v[226:227], off
	v_lshl_add_u64 v[226:227], s[24:25], 0, v[132:133]
	s_mov_b32 m0, s42
	s_nop 0
	global_load_lds_dwordx4 v[226:227], off
	s_waitcnt vmcnt(8)
	s_waitcnt lgkmcnt(0)
	s_setprio 1
	s_barrier
	v_mfma_f32_16x16x32_bf16 v[126:129], v[146:149], v[190:193], v[126:129]
	v_mfma_f32_16x16x32_bf16 v[126:129], v[150:153], v[194:197], v[126:129]
	v_mfma_f32_16x16x32_bf16 v[118:121], v[150:153], v[202:205], v[118:121]
	v_mfma_f32_16x16x32_bf16 v[118:121], v[146:149], v[198:201], v[118:121]
	v_mfma_f32_16x16x32_bf16 v[102:105], v[146:149], v[206:209], v[102:105]
	v_mfma_f32_16x16x32_bf16 v[102:105], v[150:153], v[228:231], v[102:105]
	v_mfma_f32_16x16x32_bf16 v[86:89], v[150:153], v[236:239], v[86:89]
	v_mfma_f32_16x16x32_bf16 v[86:89], v[146:149], v[232:235], v[86:89]
	v_mfma_f32_16x16x32_bf16 v[78:81], v[154:157], v[232:235], v[78:81]
	v_mfma_f32_16x16x32_bf16 v[78:81], v[158:161], v[236:239], v[78:81]
	v_mfma_f32_16x16x32_bf16 v[94:97], v[158:161], v[228:231], v[94:97]
	v_mfma_f32_16x16x32_bf16 v[94:97], v[154:157], v[206:209], v[94:97]
	v_mfma_f32_16x16x32_bf16 v[110:113], v[154:157], v[198:201], v[110:113]
	v_mfma_f32_16x16x32_bf16 v[110:113], v[158:161], v[202:205], v[110:113]
	v_mfma_f32_16x16x32_bf16 v[122:125], v[158:161], v[194:197], v[122:125]
	v_mfma_f32_16x16x32_bf16 v[122:125], v[154:157], v[190:193], v[122:125]
	v_mfma_f32_16x16x32_bf16 v[114:117], v[162:165], v[190:193], v[114:117]
	v_mfma_f32_16x16x32_bf16 v[114:117], v[166:169], v[194:197], v[114:117]
	v_mfma_f32_16x16x32_bf16 v[98:101], v[166:169], v[202:205], v[98:101]
	v_mfma_f32_16x16x32_bf16 v[98:101], v[162:165], v[198:201], v[98:101]
	v_mfma_f32_16x16x32_bf16 v[82:85], v[162:165], v[206:209], v[82:85]
	v_mfma_f32_16x16x32_bf16 v[82:85], v[166:169], v[228:231], v[82:85]
	v_mfma_f32_16x16x32_bf16 v[70:73], v[166:169], v[236:239], v[70:73]
	v_mfma_f32_16x16x32_bf16 v[70:73], v[162:165], v[232:235], v[70:73]
	v_mfma_f32_16x16x32_bf16 v[66:69], v[170:173], v[232:235], v[66:69]
	v_mfma_f32_16x16x32_bf16 v[66:69], v[178:181], v[236:239], v[66:69]
	v_mfma_f32_16x16x32_bf16 v[74:77], v[178:181], v[228:231], v[74:77]
	v_mfma_f32_16x16x32_bf16 v[74:77], v[170:173], v[206:209], v[74:77]
	v_mfma_f32_16x16x32_bf16 v[90:93], v[170:173], v[198:201], v[90:93]
	v_mfma_f32_16x16x32_bf16 v[90:93], v[178:181], v[202:205], v[90:93]
	v_mfma_f32_16x16x32_bf16 v[106:109], v[178:181], v[194:197], v[106:109]
	v_mfma_f32_16x16x32_bf16 v[106:109], v[170:173], v[190:193], v[106:109]
	s_barrier
	s_setprio 0
	s_add_i32 s24, s53, s38
	v_lshl_add_u64 v[140:141], v[140:141], 0, s[34:35]
	s_mov_b32 m0, s24
	ds_read_b128 v[190:193], v145 offset:49152
	ds_read_b128 v[194:197], v145 offset:50176
	ds_read_b128 v[198:201], v145 offset:51200
	ds_read_b128 v[202:205], v145 offset:52224
	ds_read_b128 v[206:209], v145 offset:53248
	ds_read_b128 v[228:231], v145 offset:54272
	ds_read_b128 v[232:235], v145 offset:55296
	ds_read_b128 v[236:239], v145 offset:56320
	global_load_lds_dwordx4 v[140:141], off
	s_add_i32 m0, s24, 0x2000
	s_add_u32 s22, s22, 0x100080
	v_lshl_add_u64 v[140:141], v[186:187], 0, s[34:35]
	s_addc_u32 s23, s23, 0
	s_add_i32 s24, s54, s38
	global_load_lds_dwordx4 v[140:141], off
	v_lshl_add_u64 v[140:141], s[22:23], 0, v[0:1]
	s_mov_b32 m0, s24
	s_nop 0
	global_load_lds_dwordx4 v[140:141], off
	v_lshl_add_u64 v[140:141], s[22:23], 0, v[130:131]
	s_add_i32 m0, s24, 0x2000
	s_nop 0
	global_load_lds_dwordx4 v[140:141], off
	v_lshl_add_u64 v[140:141], v[188:189], 0, s[34:35]
	s_mov_b32 m0, s43
	s_nop 0
	global_load_lds_dwordx4 v[140:141], off
	v_lshl_add_u64 v[140:141], v[210:211], 0, s[34:35]
	s_mov_b32 m0, s44
	s_nop 0
	global_load_lds_dwordx4 v[140:141], off
	s_waitcnt vmcnt(8)
	s_waitcnt lgkmcnt(0)
	s_setprio 1
	s_barrier
	v_mfma_f32_16x16x32_bf16 v[62:65], v[146:149], v[190:193], v[62:65]
	v_mfma_f32_16x16x32_bf16 v[62:65], v[150:153], v[194:197], v[62:65]
	v_mfma_f32_16x16x32_bf16 v[54:57], v[150:153], v[202:205], v[54:57]
	v_mfma_f32_16x16x32_bf16 v[54:57], v[146:149], v[198:201], v[54:57]
	v_mfma_f32_16x16x32_bf16 v[38:41], v[146:149], v[206:209], v[38:41]
	v_mfma_f32_16x16x32_bf16 v[38:41], v[150:153], v[228:231], v[38:41]
	v_mfma_f32_16x16x32_bf16 v[22:25], v[150:153], v[236:239], v[22:25]
	v_mfma_f32_16x16x32_bf16 v[22:25], v[146:149], v[232:235], v[22:25]
	v_mfma_f32_16x16x32_bf16 v[14:17], v[154:157], v[232:235], v[14:17]
	v_mfma_f32_16x16x32_bf16 v[14:17], v[158:161], v[236:239], v[14:17]
	v_mfma_f32_16x16x32_bf16 v[30:33], v[158:161], v[228:231], v[30:33]
	v_mfma_f32_16x16x32_bf16 v[30:33], v[154:157], v[206:209], v[30:33]
	v_mfma_f32_16x16x32_bf16 v[46:49], v[154:157], v[198:201], v[46:49]
	v_mfma_f32_16x16x32_bf16 v[46:49], v[158:161], v[202:205], v[46:49]
	v_mfma_f32_16x16x32_bf16 v[58:61], v[158:161], v[194:197], v[58:61]
	v_mfma_f32_16x16x32_bf16 v[58:61], v[154:157], v[190:193], v[58:61]
	v_mfma_f32_16x16x32_bf16 v[50:53], v[162:165], v[190:193], v[50:53]
	v_mfma_f32_16x16x32_bf16 v[50:53], v[166:169], v[194:197], v[50:53]
	v_mfma_f32_16x16x32_bf16 v[34:37], v[166:169], v[202:205], v[34:37]
	v_mfma_f32_16x16x32_bf16 v[34:37], v[162:165], v[198:201], v[34:37]
	v_mfma_f32_16x16x32_bf16 v[18:21], v[162:165], v[206:209], v[18:21]
	v_mfma_f32_16x16x32_bf16 v[18:21], v[166:169], v[228:231], v[18:21]
	v_mfma_f32_16x16x32_bf16 v[6:9], v[166:169], v[236:239], v[6:9]
	v_mfma_f32_16x16x32_bf16 v[6:9], v[162:165], v[232:235], v[6:9]
	v_mfma_f32_16x16x32_bf16 v[2:5], v[170:173], v[232:235], v[2:5]
	v_mfma_f32_16x16x32_bf16 v[2:5], v[178:181], v[236:239], v[2:5]
	v_mfma_f32_16x16x32_bf16 v[10:13], v[178:181], v[228:231], v[10:13]
	v_mfma_f32_16x16x32_bf16 v[10:13], v[170:173], v[206:209], v[10:13]
	v_mfma_f32_16x16x32_bf16 v[26:29], v[170:173], v[198:201], v[26:29]
	v_mfma_f32_16x16x32_bf16 v[26:29], v[178:181], v[202:205], v[26:29]
	v_mfma_f32_16x16x32_bf16 v[42:45], v[178:181], v[194:197], v[42:45]
	v_mfma_f32_16x16x32_bf16 v[42:45], v[170:173], v[190:193], v[42:45]
	s_barrier
	s_setprio 0
	s_add_i32 s52, s52, 2
	s_add_u32 s18, s18, 0x100
	s_addc_u32 s19, s19, 0
	s_add_u32 s50, s50, 0x100
	s_addc_u32 s51, s51, 0
	s_cmp_gt_u32 s52, 61
	s_cbranch_scc0 .LBB0_575
	s_and_b64 vcc, exec, s[4:5]
	s_cbranch_vccz .LBB0_578
	s_barrier

.LBB0_721:
	s_add_u32 s18, s16, 0xfff00080
	s_addc_u32 s19, s17, -1
	s_add_i32 s53, 0, 0x10000
	s_cmp_eq_u32 s52, 60
	s_cselect_b32 s23, s7, s19
	s_cselect_b32 s22, s48, s18
	v_add_u32_e32 v140, s53, v143
	s_cselect_b32 s19, s5, s51
	s_cselect_b32 s18, s49, s50
	s_add_i32 s56, 0, 0x14000
	ds_read_b128 v[146:149], v140
	ds_read_b128 v[150:153], v140 offset:1024
	ds_read_b128 v[154:157], v140 offset:2048
	ds_read_b128 v[158:161], v140 offset:3072
	v_add_u32_e32 v140, s56, v143
	ds_read_b128 v[162:165], v140
	ds_read_b128 v[166:169], v140 offset:1024
	ds_read_b128 v[170:173], v140 offset:2048
	ds_read_b128 v[178:181], v140 offset:3072
	v_lshl_add_u64 v[140:141], s[16:17], 0, v[136:137]
	s_add_i32 m0, s31, 0xc000
	ds_read_b128 v[190:193], v145
	ds_read_b128 v[194:197], v145 offset:1024
	ds_read_b128 v[198:201], v145 offset:2048
	ds_read_b128 v[202:205], v145 offset:3072
	ds_read_b128 v[206:209], v145 offset:4096
	ds_read_b128 v[228:231], v145 offset:5120
	ds_read_b128 v[232:235], v145 offset:6144
	ds_read_b128 v[236:239], v145 offset:7168
	global_load_lds_dwordx4 v[140:141], off
	v_lshl_add_u64 v[140:141], s[16:17], 0, v[138:139]
	s_add_i32 m0, s31, 0xe000
	s_nop 0
	global_load_lds_dwordx4 v[140:141], off
	s_waitcnt vmcnt(8)
	s_waitcnt lgkmcnt(0)
	s_setprio 1
	s_barrier
	v_mfma_f32_16x16x32_bf16 v[126:129], v[146:149], v[190:193], v[126:129]
	v_mfma_f32_16x16x32_bf16 v[126:129], v[150:153], v[194:197], v[126:129]
	v_mfma_f32_16x16x32_bf16 v[110:113], v[150:153], v[202:205], v[110:113]
	v_mfma_f32_16x16x32_bf16 v[110:113], v[146:149], v[198:201], v[110:113]
	v_mfma_f32_16x16x32_bf16 v[94:97], v[146:149], v[206:209], v[94:97]
	v_mfma_f32_16x16x32_bf16 v[94:97], v[150:153], v[228:231], v[94:97]
	v_mfma_f32_16x16x32_bf16 v[78:81], v[150:153], v[236:239], v[78:81]
	v_mfma_f32_16x16x32_bf16 v[78:81], v[146:149], v[232:235], v[78:81]
	v_mfma_f32_16x16x32_bf16 v[70:73], v[154:157], v[232:235], v[70:73]
	v_mfma_f32_16x16x32_bf16 v[70:73], v[158:161], v[236:239], v[70:73]
	v_mfma_f32_16x16x32_bf16 v[86:89], v[158:161], v[228:231], v[86:89]
	v_mfma_f32_16x16x32_bf16 v[86:89], v[154:157], v[206:209], v[86:89]
	v_mfma_f32_16x16x32_bf16 v[102:105], v[154:157], v[198:201], v[102:105]
	v_mfma_f32_16x16x32_bf16 v[102:105], v[158:161], v[202:205], v[102:105]
	v_mfma_f32_16x16x32_bf16 v[118:121], v[158:161], v[194:197], v[118:121]
	v_mfma_f32_16x16x32_bf16 v[118:121], v[154:157], v[190:193], v[118:121]
	v_mfma_f32_16x16x32_bf16 v[122:125], v[162:165], v[190:193], v[122:125]
	v_mfma_f32_16x16x32_bf16 v[122:125], v[166:169], v[194:197], v[122:125]
	v_mfma_f32_16x16x32_bf16 v[106:109], v[166:169], v[202:205], v[106:109]
	v_mfma_f32_16x16x32_bf16 v[106:109], v[162:165], v[198:201], v[106:109]
	v_mfma_f32_16x16x32_bf16 v[90:93], v[162:165], v[206:209], v[90:93]
	v_mfma_f32_16x16x32_bf16 v[90:93], v[166:169], v[228:231], v[90:93]
	v_mfma_f32_16x16x32_bf16 v[74:77], v[166:169], v[236:239], v[74:77]
	v_mfma_f32_16x16x32_bf16 v[74:77], v[162:165], v[232:235], v[74:77]
	v_mfma_f32_16x16x32_bf16 v[66:69], v[170:173], v[232:235], v[66:69]
	v_mfma_f32_16x16x32_bf16 v[66:69], v[178:181], v[236:239], v[66:69]
	v_mfma_f32_16x16x32_bf16 v[82:85], v[178:181], v[228:231], v[82:85]
	v_mfma_f32_16x16x32_bf16 v[82:85], v[170:173], v[206:209], v[82:85]
	v_mfma_f32_16x16x32_bf16 v[98:101], v[170:173], v[198:201], v[98:101]
	v_mfma_f32_16x16x32_bf16 v[98:101], v[178:181], v[202:205], v[98:101]
	v_mfma_f32_16x16x32_bf16 v[114:117], v[178:181], v[194:197], v[114:117]
	v_mfma_f32_16x16x32_bf16 v[114:117], v[170:173], v[190:193], v[114:117]
	s_barrier
	s_setprio 0
	s_add_i32 s53, s53, s26
	v_lshl_add_u64 v[140:141], s[18:19], 0, v[0:1]
	s_mov_b32 m0, s53
	ds_read_b128 v[190:193], v145 offset:16384
	ds_read_b128 v[194:197], v145 offset:17408
	ds_read_b128 v[198:201], v145 offset:18432
	ds_read_b128 v[202:205], v145 offset:19456
	ds_read_b128 v[206:209], v145 offset:20480
	ds_read_b128 v[228:231], v145 offset:21504
	ds_read_b128 v[232:235], v145 offset:22528
	ds_read_b128 v[236:239], v145 offset:23552
	global_load_lds_dwordx4 v[140:141], off
	s_add_i32 m0, s53, 0x2000
	s_add_u32 s54, s18, 0x100000
	v_lshl_add_u64 v[186:187], s[18:19], 0, v[130:131]
	s_addc_u32 s55, s19, 0
	s_add_i32 s53, s56, s26
	global_load_lds_dwordx4 v[186:187], off
	v_lshl_add_u64 v[188:189], s[54:55], 0, v[0:1]
	s_mov_b32 m0, s53
	v_lshl_add_u64 v[210:211], s[22:23], 0, v[132:133]
	global_load_lds_dwordx4 v[188:189], off
	v_lshl_add_u64 v[188:189], s[54:55], 0, v[130:131]
	s_add_i32 m0, s53, 0x2000
	s_nop 0
	global_load_lds_dwordx4 v[188:189], off
	v_lshl_add_u64 v[188:189], s[22:23], 0, v[134:135]
	s_mov_b32 m0, s31
	s_nop 0
	global_load_lds_dwordx4 v[188:189], off
	s_mov_b32 m0, s40
	s_nop 0
	global_load_lds_dwordx4 v[210:211], off
	s_waitcnt vmcnt(8)
	s_waitcnt lgkmcnt(0)
	s_setprio 1
	s_barrier
	v_mfma_f32_16x16x32_bf16 v[62:65], v[146:149], v[190:193], v[62:65]
	v_mfma_f32_16x16x32_bf16 v[62:65], v[150:153], v[194:197], v[62:65]
	v_mfma_f32_16x16x32_bf16 v[46:49], v[150:153], v[202:205], v[46:49]
	v_mfma_f32_16x16x32_bf16 v[46:49], v[146:149], v[198:201], v[46:49]
	v_mfma_f32_16x16x32_bf16 v[30:33], v[146:149], v[206:209], v[30:33]
	v_mfma_f32_16x16x32_bf16 v[30:33], v[150:153], v[228:231], v[30:33]
	v_mfma_f32_16x16x32_bf16 v[14:17], v[150:153], v[236:239], v[14:17]
	v_mfma_f32_16x16x32_bf16 v[14:17], v[146:149], v[232:235], v[14:17]
	v_mfma_f32_16x16x32_bf16 v[6:9], v[154:157], v[232:235], v[6:9]
	v_mfma_f32_16x16x32_bf16 v[6:9], v[158:161], v[236:239], v[6:9]
	v_mfma_f32_16x16x32_bf16 v[22:25], v[158:161], v[228:231], v[22:25]
	v_mfma_f32_16x16x32_bf16 v[22:25], v[154:157], v[206:209], v[22:25]
	v_mfma_f32_16x16x32_bf16 v[38:41], v[154:157], v[198:201], v[38:41]
	v_mfma_f32_16x16x32_bf16 v[38:41], v[158:161], v[202:205], v[38:41]
	v_mfma_f32_16x16x32_bf16 v[54:57], v[158:161], v[194:197], v[54:57]
	v_mfma_f32_16x16x32_bf16 v[54:57], v[154:157], v[190:193], v[54:57]
	v_mfma_f32_16x16x32_bf16 v[58:61], v[162:165], v[190:193], v[58:61]
	v_mfma_f32_16x16x32_bf16 v[58:61], v[166:169], v[194:197], v[58:61]
	v_mfma_f32_16x16x32_bf16 v[42:45], v[166:169], v[202:205], v[42:45]
	v_mfma_f32_16x16x32_bf16 v[42:45], v[162:165], v[198:201], v[42:45]
	v_mfma_f32_16x16x32_bf16 v[26:29], v[162:165], v[206:209], v[26:29]
	v_mfma_f32_16x16x32_bf16 v[26:29], v[166:169], v[228:231], v[26:29]
	v_mfma_f32_16x16x32_bf16 v[10:13], v[166:169], v[236:239], v[10:13]
	v_mfma_f32_16x16x32_bf16 v[10:13], v[162:165], v[232:235], v[10:13]
	v_mfma_f32_16x16x32_bf16 v[2:5], v[170:173], v[232:235], v[2:5]
	v_mfma_f32_16x16x32_bf16 v[2:5], v[178:181], v[236:239], v[2:5]
	v_mfma_f32_16x16x32_bf16 v[18:21], v[178:181], v[228:231], v[18:21]
	v_mfma_f32_16x16x32_bf16 v[18:21], v[170:173], v[206:209], v[18:21]
	v_mfma_f32_16x16x32_bf16 v[34:37], v[170:173], v[198:201], v[34:37]
	v_mfma_f32_16x16x32_bf16 v[34:37], v[178:181], v[202:205], v[34:37]
	v_mfma_f32_16x16x32_bf16 v[50:53], v[178:181], v[194:197], v[50:53]
	v_mfma_f32_16x16x32_bf16 v[50:53], v[170:173], v[190:193], v[50:53]
	s_barrier
	s_setprio 0
	s_add_i32 s53, 0, 0x18000
	s_add_i32 s54, 0, 0x1c000
	v_add_u32_e32 v158, s53, v143
	v_add_u32_e32 v175, s54, v143
	ds_read_b128 v[146:149], v158
	ds_read_b128 v[150:153], v158 offset:1024
	ds_read_b128 v[154:157], v158 offset:2048
	ds_read_b128 v[158:161], v158 offset:3072
	ds_read_b128 v[162:165], v175
	ds_read_b128 v[166:169], v175 offset:1024
	ds_read_b128 v[170:173], v175 offset:2048
	ds_read_b128 v[178:181], v175 offset:3072
	s_add_u32 s22, s22, 0x100000
	s_addc_u32 s23, s23, 0
	s_mov_b32 m0, s41
	v_lshl_add_u64 v[226:227], s[22:23], 0, v[134:135]
	ds_read_b128 v[190:193], v145 offset:32768
	ds_read_b128 v[194:197], v145 offset:33792
	ds_read_b128 v[198:201], v145 offset:34816
	ds_read_b128 v[202:205], v145 offset:35840
	ds_read_b128 v[206:209], v145 offset:36864
	ds_read_b128 v[228:231], v145 offset:37888
	ds_read_b128 v[232:235], v145 offset:38912
	ds_read_b128 v[236:239], v145 offset:39936
	global_load_lds_dwordx4 v[226:227], off
	v_lshl_add_u64 v[226:227], s[22:23], 0, v[132:133]
	s_mov_b32 m0, s42
	s_nop 0
	global_load_lds_dwordx4 v[226:227], off
	s_waitcnt vmcnt(8)
	s_waitcnt lgkmcnt(0)
	s_setprio 1
	s_barrier
	v_mfma_f32_16x16x32_bf16 v[126:129], v[146:149], v[190:193], v[126:129]
	v_mfma_f32_16x16x32_bf16 v[126:129], v[150:153], v[194:197], v[126:129]
	v_mfma_f32_16x16x32_bf16 v[110:113], v[150:153], v[202:205], v[110:113]
	v_mfma_f32_16x16x32_bf16 v[110:113], v[146:149], v[198:201], v[110:113]
	v_mfma_f32_16x16x32_bf16 v[94:97], v[146:149], v[206:209], v[94:97]
	v_mfma_f32_16x16x32_bf16 v[94:97], v[150:153], v[228:231], v[94:97]
	v_mfma_f32_16x16x32_bf16 v[78:81], v[150:153], v[236:239], v[78:81]
	v_mfma_f32_16x16x32_bf16 v[78:81], v[146:149], v[232:235], v[78:81]
	v_mfma_f32_16x16x32_bf16 v[70:73], v[154:157], v[232:235], v[70:73]
	v_mfma_f32_16x16x32_bf16 v[70:73], v[158:161], v[236:239], v[70:73]
	v_mfma_f32_16x16x32_bf16 v[86:89], v[158:161], v[228:231], v[86:89]
	v_mfma_f32_16x16x32_bf16 v[86:89], v[154:157], v[206:209], v[86:89]
	v_mfma_f32_16x16x32_bf16 v[102:105], v[154:157], v[198:201], v[102:105]
	v_mfma_f32_16x16x32_bf16 v[102:105], v[158:161], v[202:205], v[102:105]
	v_mfma_f32_16x16x32_bf16 v[118:121], v[158:161], v[194:197], v[118:121]
	v_mfma_f32_16x16x32_bf16 v[118:121], v[154:157], v[190:193], v[118:121]
	v_mfma_f32_16x16x32_bf16 v[122:125], v[162:165], v[190:193], v[122:125]
	v_mfma_f32_16x16x32_bf16 v[122:125], v[166:169], v[194:197], v[122:125]
	v_mfma_f32_16x16x32_bf16 v[106:109], v[166:169], v[202:205], v[106:109]
	v_mfma_f32_16x16x32_bf16 v[106:109], v[162:165], v[198:201], v[106:109]
	v_mfma_f32_16x16x32_bf16 v[90:93], v[162:165], v[206:209], v[90:93]
	v_mfma_f32_16x16x32_bf16 v[90:93], v[166:169], v[228:231], v[90:93]
	v_mfma_f32_16x16x32_bf16 v[74:77], v[166:169], v[236:239], v[74:77]
	v_mfma_f32_16x16x32_bf16 v[74:77], v[162:165], v[232:235], v[74:77]
	v_mfma_f32_16x16x32_bf16 v[66:69], v[170:173], v[232:235], v[66:69]
	v_mfma_f32_16x16x32_bf16 v[66:69], v[178:181], v[236:239], v[66:69]
	v_mfma_f32_16x16x32_bf16 v[82:85], v[178:181], v[228:231], v[82:85]
	v_mfma_f32_16x16x32_bf16 v[82:85], v[170:173], v[206:209], v[82:85]
	v_mfma_f32_16x16x32_bf16 v[98:101], v[170:173], v[198:201], v[98:101]
	v_mfma_f32_16x16x32_bf16 v[98:101], v[178:181], v[202:205], v[98:101]
	v_mfma_f32_16x16x32_bf16 v[114:117], v[178:181], v[194:197], v[114:117]
	v_mfma_f32_16x16x32_bf16 v[114:117], v[170:173], v[190:193], v[114:117]
	s_barrier
	s_setprio 0
	s_add_i32 s22, s53, s26
	v_lshl_add_u64 v[140:141], v[140:141], 0, s[34:35]
	s_mov_b32 m0, s22
	ds_read_b128 v[190:193], v145 offset:49152
	ds_read_b128 v[194:197], v145 offset:50176
	ds_read_b128 v[198:201], v145 offset:51200
	ds_read_b128 v[202:205], v145 offset:52224
	ds_read_b128 v[206:209], v145 offset:53248
	ds_read_b128 v[228:231], v145 offset:54272
	ds_read_b128 v[232:235], v145 offset:55296
	ds_read_b128 v[236:239], v145 offset:56320
	global_load_lds_dwordx4 v[140:141], off
	s_add_i32 m0, s22, 0x2000
	s_add_u32 s18, s18, 0x100080
	v_lshl_add_u64 v[140:141], v[186:187], 0, s[34:35]
	s_addc_u32 s19, s19, 0
	s_add_i32 s22, s54, s26
	global_load_lds_dwordx4 v[140:141], off
	v_lshl_add_u64 v[140:141], s[18:19], 0, v[0:1]
	s_mov_b32 m0, s22
	s_nop 0
	global_load_lds_dwordx4 v[140:141], off
	v_lshl_add_u64 v[140:141], s[18:19], 0, v[130:131]
	s_add_i32 m0, s22, 0x2000
	s_nop 0
	global_load_lds_dwordx4 v[140:141], off
	v_lshl_add_u64 v[140:141], v[188:189], 0, s[34:35]
	s_mov_b32 m0, s43
	s_nop 0
	global_load_lds_dwordx4 v[140:141], off
	v_lshl_add_u64 v[140:141], v[210:211], 0, s[34:35]
	s_mov_b32 m0, s44
	s_nop 0
	global_load_lds_dwordx4 v[140:141], off
	s_waitcnt vmcnt(8)
	s_waitcnt lgkmcnt(0)
	s_setprio 1
	s_barrier
	v_mfma_f32_16x16x32_bf16 v[62:65], v[146:149], v[190:193], v[62:65]
	v_mfma_f32_16x16x32_bf16 v[62:65], v[150:153], v[194:197], v[62:65]
	v_mfma_f32_16x16x32_bf16 v[46:49], v[150:153], v[202:205], v[46:49]
	v_mfma_f32_16x16x32_bf16 v[46:49], v[146:149], v[198:201], v[46:49]
	v_mfma_f32_16x16x32_bf16 v[30:33], v[146:149], v[206:209], v[30:33]
	v_mfma_f32_16x16x32_bf16 v[30:33], v[150:153], v[228:231], v[30:33]
	v_mfma_f32_16x16x32_bf16 v[14:17], v[150:153], v[236:239], v[14:17]
	v_mfma_f32_16x16x32_bf16 v[14:17], v[146:149], v[232:235], v[14:17]
	v_mfma_f32_16x16x32_bf16 v[6:9], v[154:157], v[232:235], v[6:9]
	v_mfma_f32_16x16x32_bf16 v[6:9], v[158:161], v[236:239], v[6:9]
	v_mfma_f32_16x16x32_bf16 v[22:25], v[158:161], v[228:231], v[22:25]
	v_mfma_f32_16x16x32_bf16 v[22:25], v[154:157], v[206:209], v[22:25]
	v_mfma_f32_16x16x32_bf16 v[38:41], v[154:157], v[198:201], v[38:41]
	v_mfma_f32_16x16x32_bf16 v[38:41], v[158:161], v[202:205], v[38:41]
	v_mfma_f32_16x16x32_bf16 v[54:57], v[158:161], v[194:197], v[54:57]
	v_mfma_f32_16x16x32_bf16 v[54:57], v[154:157], v[190:193], v[54:57]
	v_mfma_f32_16x16x32_bf16 v[58:61], v[162:165], v[190:193], v[58:61]
	v_mfma_f32_16x16x32_bf16 v[58:61], v[166:169], v[194:197], v[58:61]
	v_mfma_f32_16x16x32_bf16 v[42:45], v[166:169], v[202:205], v[42:45]
	v_mfma_f32_16x16x32_bf16 v[42:45], v[162:165], v[198:201], v[42:45]
	v_mfma_f32_16x16x32_bf16 v[26:29], v[162:165], v[206:209], v[26:29]
	v_mfma_f32_16x16x32_bf16 v[26:29], v[166:169], v[228:231], v[26:29]
	v_mfma_f32_16x16x32_bf16 v[10:13], v[166:169], v[236:239], v[10:13]
	v_mfma_f32_16x16x32_bf16 v[10:13], v[162:165], v[232:235], v[10:13]
	v_mfma_f32_16x16x32_bf16 v[2:5], v[170:173], v[232:235], v[2:5]
	v_mfma_f32_16x16x32_bf16 v[2:5], v[178:181], v[236:239], v[2:5]
	v_mfma_f32_16x16x32_bf16 v[18:21], v[178:181], v[228:231], v[18:21]
	v_mfma_f32_16x16x32_bf16 v[18:21], v[170:173], v[206:209], v[18:21]
	v_mfma_f32_16x16x32_bf16 v[34:37], v[170:173], v[198:201], v[34:37]
	v_mfma_f32_16x16x32_bf16 v[34:37], v[178:181], v[202:205], v[34:37]
	v_mfma_f32_16x16x32_bf16 v[50:53], v[178:181], v[194:197], v[50:53]
	v_mfma_f32_16x16x32_bf16 v[50:53], v[170:173], v[190:193], v[50:53]
	s_barrier
	s_setprio 0
	s_add_i32 s52, s52, 2
	s_add_u32 s16, s16, 0x100
	s_addc_u32 s17, s17, 0
	s_add_u32 s50, s50, 0x100
	s_addc_u32 s51, s51, 0
	s_cmp_gt_u32 s52, 61
	s_cbranch_scc0 .LBB0_721
	s_and_b64 vcc, exec, s[2:3]
	s_cbranch_vccz .LBB0_724
	s_barrier

.LBB0_805:
	s_add_u32 s16, s14, 0x100
	s_addc_u32 s17, s15, 0
	s_add_i32 s49, 0, 0x10000
	s_cmpk_eq_i32 s48, 0xa8
	s_cselect_b32 s23, s5, s17
	s_cselect_b32 s22, s4, s16
	v_add_u32_e32 v140, s49, v143
	s_cselect_b32 s19, s9, s47
	s_cselect_b32 s18, s8, s46
	s_add_i32 s50, 0, 0x14000
	ds_read_b128 v[146:149], v140
	ds_read_b128 v[150:153], v140 offset:1024
	ds_read_b128 v[154:157], v140 offset:2048
	ds_read_b128 v[158:161], v140 offset:3072
	v_add_u32_e32 v140, s50, v143
	ds_read_b128 v[162:165], v140
	ds_read_b128 v[166:169], v140 offset:1024
	ds_read_b128 v[170:173], v140 offset:2048
	ds_read_b128 v[178:181], v140 offset:3072
	v_lshl_add_u64 v[140:141], s[14:15], 0, v[136:137]
	s_add_i32 m0, s31, 0xc000
	ds_read_b128 v[190:193], v145
	ds_read_b128 v[194:197], v145 offset:1024
	ds_read_b128 v[198:201], v145 offset:2048
	ds_read_b128 v[202:205], v145 offset:3072
	ds_read_b128 v[206:209], v145 offset:4096
	ds_read_b128 v[228:231], v145 offset:5120
	ds_read_b128 v[232:235], v145 offset:6144
	ds_read_b128 v[236:239], v145 offset:7168
	global_load_lds_dwordx4 v[140:141], off
	v_lshl_add_u64 v[140:141], s[14:15], 0, v[138:139]
	s_add_i32 m0, s31, 0xe000
	s_nop 0
	global_load_lds_dwordx4 v[140:141], off
	s_waitcnt vmcnt(8)
	s_waitcnt lgkmcnt(0)
	s_setprio 1
	s_barrier
	v_mfma_f32_16x16x32_bf16 v[126:129], v[146:149], v[190:193], v[126:129]
	v_mfma_f32_16x16x32_bf16 v[126:129], v[150:153], v[194:197], v[126:129]
	v_mfma_f32_16x16x32_bf16 v[118:121], v[150:153], v[202:205], v[118:121]
	v_mfma_f32_16x16x32_bf16 v[118:121], v[146:149], v[198:201], v[118:121]
	v_mfma_f32_16x16x32_bf16 v[102:105], v[146:149], v[206:209], v[102:105]
	v_mfma_f32_16x16x32_bf16 v[102:105], v[150:153], v[228:231], v[102:105]
	v_mfma_f32_16x16x32_bf16 v[86:89], v[150:153], v[236:239], v[86:89]
	v_mfma_f32_16x16x32_bf16 v[86:89], v[146:149], v[232:235], v[86:89]
	v_mfma_f32_16x16x32_bf16 v[78:81], v[154:157], v[232:235], v[78:81]
	v_mfma_f32_16x16x32_bf16 v[78:81], v[158:161], v[236:239], v[78:81]
	v_mfma_f32_16x16x32_bf16 v[94:97], v[158:161], v[228:231], v[94:97]
	v_mfma_f32_16x16x32_bf16 v[94:97], v[154:157], v[206:209], v[94:97]
	v_mfma_f32_16x16x32_bf16 v[110:113], v[154:157], v[198:201], v[110:113]
	v_mfma_f32_16x16x32_bf16 v[110:113], v[158:161], v[202:205], v[110:113]
	v_mfma_f32_16x16x32_bf16 v[122:125], v[158:161], v[194:197], v[122:125]
	v_mfma_f32_16x16x32_bf16 v[122:125], v[154:157], v[190:193], v[122:125]
	v_mfma_f32_16x16x32_bf16 v[114:117], v[162:165], v[190:193], v[114:117]
	v_mfma_f32_16x16x32_bf16 v[114:117], v[166:169], v[194:197], v[114:117]
	v_mfma_f32_16x16x32_bf16 v[98:101], v[166:169], v[202:205], v[98:101]
	v_mfma_f32_16x16x32_bf16 v[98:101], v[162:165], v[198:201], v[98:101]
	v_mfma_f32_16x16x32_bf16 v[82:85], v[162:165], v[206:209], v[82:85]
	v_mfma_f32_16x16x32_bf16 v[82:85], v[166:169], v[228:231], v[82:85]
	v_mfma_f32_16x16x32_bf16 v[70:73], v[166:169], v[236:239], v[70:73]
	v_mfma_f32_16x16x32_bf16 v[70:73], v[162:165], v[232:235], v[70:73]
	v_mfma_f32_16x16x32_bf16 v[66:69], v[170:173], v[232:235], v[66:69]
	v_mfma_f32_16x16x32_bf16 v[66:69], v[178:181], v[236:239], v[66:69]
	v_mfma_f32_16x16x32_bf16 v[74:77], v[178:181], v[228:231], v[74:77]
	v_mfma_f32_16x16x32_bf16 v[74:77], v[170:173], v[206:209], v[74:77]
	v_mfma_f32_16x16x32_bf16 v[90:93], v[170:173], v[198:201], v[90:93]
	v_mfma_f32_16x16x32_bf16 v[90:93], v[178:181], v[202:205], v[90:93]
	v_mfma_f32_16x16x32_bf16 v[106:109], v[178:181], v[194:197], v[106:109]
	v_mfma_f32_16x16x32_bf16 v[106:109], v[170:173], v[190:193], v[106:109]
	s_barrier
	s_setprio 0
	s_add_i32 s14, s49, s26
	v_lshl_add_u64 v[140:141], s[18:19], 0, v[0:1]
	s_mov_b32 m0, s14
	ds_read_b128 v[190:193], v145 offset:16384
	ds_read_b128 v[194:197], v145 offset:17408
	ds_read_b128 v[198:201], v145 offset:18432
	ds_read_b128 v[202:205], v145 offset:19456
	ds_read_b128 v[206:209], v145 offset:20480
	ds_read_b128 v[228:231], v145 offset:21504
	ds_read_b128 v[232:235], v145 offset:22528
	ds_read_b128 v[236:239], v145 offset:23552
	global_load_lds_dwordx4 v[140:141], off
	s_add_i32 m0, s14, 0x2000
	s_add_u32 s14, s18, 0x2b0000
	v_lshl_add_u64 v[186:187], s[18:19], 0, v[130:131]
	s_addc_u32 s15, s19, 0
	s_add_i32 s49, s50, s26
	global_load_lds_dwordx4 v[186:187], off
	v_lshl_add_u64 v[188:189], s[14:15], 0, v[0:1]
	s_mov_b32 m0, s49
	v_lshl_add_u64 v[210:211], s[22:23], 0, v[132:133]
	global_load_lds_dwordx4 v[188:189], off
	v_lshl_add_u64 v[188:189], s[14:15], 0, v[130:131]
	s_add_i32 m0, s49, 0x2000
	s_nop 0
	global_load_lds_dwordx4 v[188:189], off
	v_lshl_add_u64 v[188:189], s[22:23], 0, v[134:135]
	s_mov_b32 m0, s31
	s_nop 0
	global_load_lds_dwordx4 v[188:189], off
	s_mov_b32 m0, s36
	s_nop 0
	global_load_lds_dwordx4 v[210:211], off
	s_waitcnt vmcnt(8)
	s_waitcnt lgkmcnt(0)
	s_setprio 1
	s_barrier
	v_mfma_f32_16x16x32_bf16 v[62:65], v[146:149], v[190:193], v[62:65]
	v_mfma_f32_16x16x32_bf16 v[62:65], v[150:153], v[194:197], v[62:65]
	v_mfma_f32_16x16x32_bf16 v[54:57], v[150:153], v[202:205], v[54:57]
	v_mfma_f32_16x16x32_bf16 v[54:57], v[146:149], v[198:201], v[54:57]
	v_mfma_f32_16x16x32_bf16 v[38:41], v[146:149], v[206:209], v[38:41]
	v_mfma_f32_16x16x32_bf16 v[38:41], v[150:153], v[228:231], v[38:41]
	v_mfma_f32_16x16x32_bf16 v[22:25], v[150:153], v[236:239], v[22:25]
	v_mfma_f32_16x16x32_bf16 v[22:25], v[146:149], v[232:235], v[22:25]
	v_mfma_f32_16x16x32_bf16 v[14:17], v[154:157], v[232:235], v[14:17]
	v_mfma_f32_16x16x32_bf16 v[14:17], v[158:161], v[236:239], v[14:17]
	v_mfma_f32_16x16x32_bf16 v[30:33], v[158:161], v[228:231], v[30:33]
	v_mfma_f32_16x16x32_bf16 v[30:33], v[154:157], v[206:209], v[30:33]
	v_mfma_f32_16x16x32_bf16 v[46:49], v[154:157], v[198:201], v[46:49]
	v_mfma_f32_16x16x32_bf16 v[46:49], v[158:161], v[202:205], v[46:49]
	v_mfma_f32_16x16x32_bf16 v[58:61], v[158:161], v[194:197], v[58:61]
	v_mfma_f32_16x16x32_bf16 v[58:61], v[154:157], v[190:193], v[58:61]
	v_mfma_f32_16x16x32_bf16 v[50:53], v[162:165], v[190:193], v[50:53]
	v_mfma_f32_16x16x32_bf16 v[50:53], v[166:169], v[194:197], v[50:53]
	v_mfma_f32_16x16x32_bf16 v[34:37], v[166:169], v[202:205], v[34:37]
	v_mfma_f32_16x16x32_bf16 v[34:37], v[162:165], v[198:201], v[34:37]
	v_mfma_f32_16x16x32_bf16 v[18:21], v[162:165], v[206:209], v[18:21]
	v_mfma_f32_16x16x32_bf16 v[18:21], v[166:169], v[228:231], v[18:21]
	v_mfma_f32_16x16x32_bf16 v[6:9], v[166:169], v[236:239], v[6:9]
	v_mfma_f32_16x16x32_bf16 v[6:9], v[162:165], v[232:235], v[6:9]
	v_mfma_f32_16x16x32_bf16 v[2:5], v[170:173], v[232:235], v[2:5]
	v_mfma_f32_16x16x32_bf16 v[2:5], v[178:181], v[236:239], v[2:5]
	v_mfma_f32_16x16x32_bf16 v[10:13], v[178:181], v[228:231], v[10:13]
	v_mfma_f32_16x16x32_bf16 v[10:13], v[170:173], v[206:209], v[10:13]
	v_mfma_f32_16x16x32_bf16 v[26:29], v[170:173], v[198:201], v[26:29]
	v_mfma_f32_16x16x32_bf16 v[26:29], v[178:181], v[202:205], v[26:29]
	v_mfma_f32_16x16x32_bf16 v[42:45], v[178:181], v[194:197], v[42:45]
	v_mfma_f32_16x16x32_bf16 v[42:45], v[170:173], v[190:193], v[42:45]
	s_barrier
	s_setprio 0
	s_add_i32 s49, 0, 0x18000
	s_add_i32 s50, 0, 0x1c000
	v_add_u32_e32 v158, s49, v143
	v_add_u32_e32 v175, s50, v143
	ds_read_b128 v[146:149], v158
	ds_read_b128 v[150:153], v158 offset:1024
	ds_read_b128 v[154:157], v158 offset:2048
	ds_read_b128 v[158:161], v158 offset:3072
	ds_read_b128 v[162:165], v175
	ds_read_b128 v[166:169], v175 offset:1024
	ds_read_b128 v[170:173], v175 offset:2048
	ds_read_b128 v[178:181], v175 offset:3072
	s_add_u32 s14, s22, 0x2b0000
	s_addc_u32 s15, s23, 0
	s_mov_b32 m0, s37
	v_lshl_add_u64 v[226:227], s[14:15], 0, v[134:135]
	ds_read_b128 v[190:193], v145 offset:32768
	ds_read_b128 v[194:197], v145 offset:33792
	ds_read_b128 v[198:201], v145 offset:34816
	ds_read_b128 v[202:205], v145 offset:35840
	ds_read_b128 v[206:209], v145 offset:36864
	ds_read_b128 v[228:231], v145 offset:37888
	ds_read_b128 v[232:235], v145 offset:38912
	ds_read_b128 v[236:239], v145 offset:39936
	global_load_lds_dwordx4 v[226:227], off
	v_lshl_add_u64 v[226:227], s[14:15], 0, v[132:133]
	s_mov_b32 m0, s38
	s_nop 0
	global_load_lds_dwordx4 v[226:227], off
	s_waitcnt vmcnt(8)
	s_waitcnt lgkmcnt(0)
	s_setprio 1
	s_barrier
	v_mfma_f32_16x16x32_bf16 v[126:129], v[146:149], v[190:193], v[126:129]
	v_mfma_f32_16x16x32_bf16 v[126:129], v[150:153], v[194:197], v[126:129]
	v_mfma_f32_16x16x32_bf16 v[118:121], v[150:153], v[202:205], v[118:121]
	v_mfma_f32_16x16x32_bf16 v[118:121], v[146:149], v[198:201], v[118:121]
	v_mfma_f32_16x16x32_bf16 v[102:105], v[146:149], v[206:209], v[102:105]
	v_mfma_f32_16x16x32_bf16 v[102:105], v[150:153], v[228:231], v[102:105]
	v_mfma_f32_16x16x32_bf16 v[86:89], v[150:153], v[236:239], v[86:89]
	v_mfma_f32_16x16x32_bf16 v[86:89], v[146:149], v[232:235], v[86:89]
	v_mfma_f32_16x16x32_bf16 v[78:81], v[154:157], v[232:235], v[78:81]
	v_mfma_f32_16x16x32_bf16 v[78:81], v[158:161], v[236:239], v[78:81]
	v_mfma_f32_16x16x32_bf16 v[94:97], v[158:161], v[228:231], v[94:97]
	v_mfma_f32_16x16x32_bf16 v[94:97], v[154:157], v[206:209], v[94:97]
	v_mfma_f32_16x16x32_bf16 v[110:113], v[154:157], v[198:201], v[110:113]
	v_mfma_f32_16x16x32_bf16 v[110:113], v[158:161], v[202:205], v[110:113]
	v_mfma_f32_16x16x32_bf16 v[122:125], v[158:161], v[194:197], v[122:125]
	v_mfma_f32_16x16x32_bf16 v[122:125], v[154:157], v[190:193], v[122:125]
	v_mfma_f32_16x16x32_bf16 v[114:117], v[162:165], v[190:193], v[114:117]
	v_mfma_f32_16x16x32_bf16 v[114:117], v[166:169], v[194:197], v[114:117]
	v_mfma_f32_16x16x32_bf16 v[98:101], v[166:169], v[202:205], v[98:101]
	v_mfma_f32_16x16x32_bf16 v[98:101], v[162:165], v[198:201], v[98:101]
	v_mfma_f32_16x16x32_bf16 v[82:85], v[162:165], v[206:209], v[82:85]
	v_mfma_f32_16x16x32_bf16 v[82:85], v[166:169], v[228:231], v[82:85]
	v_mfma_f32_16x16x32_bf16 v[70:73], v[166:169], v[236:239], v[70:73]
	v_mfma_f32_16x16x32_bf16 v[70:73], v[162:165], v[232:235], v[70:73]
	v_mfma_f32_16x16x32_bf16 v[66:69], v[170:173], v[232:235], v[66:69]
	v_mfma_f32_16x16x32_bf16 v[66:69], v[178:181], v[236:239], v[66:69]
	v_mfma_f32_16x16x32_bf16 v[74:77], v[178:181], v[228:231], v[74:77]
	v_mfma_f32_16x16x32_bf16 v[74:77], v[170:173], v[206:209], v[74:77]
	v_mfma_f32_16x16x32_bf16 v[90:93], v[170:173], v[198:201], v[90:93]
	v_mfma_f32_16x16x32_bf16 v[90:93], v[178:181], v[202:205], v[90:93]
	v_mfma_f32_16x16x32_bf16 v[106:109], v[178:181], v[194:197], v[106:109]
	v_mfma_f32_16x16x32_bf16 v[106:109], v[170:173], v[190:193], v[106:109]
	s_barrier
	s_setprio 0
	s_add_i32 s14, s49, s26
	v_lshl_add_u64 v[140:141], v[140:141], 0, s[34:35]
	s_mov_b32 m0, s14
	ds_read_b128 v[190:193], v145 offset:49152
	ds_read_b128 v[194:197], v145 offset:50176
	ds_read_b128 v[198:201], v145 offset:51200
	ds_read_b128 v[202:205], v145 offset:52224
	ds_read_b128 v[206:209], v145 offset:53248
	ds_read_b128 v[228:231], v145 offset:54272
	ds_read_b128 v[232:235], v145 offset:55296
	ds_read_b128 v[236:239], v145 offset:56320
	global_load_lds_dwordx4 v[140:141], off
	s_add_i32 m0, s14, 0x2000
	s_add_u32 s14, s18, 0x2b0080
	v_lshl_add_u64 v[140:141], v[186:187], 0, s[34:35]
	s_addc_u32 s15, s19, 0
	s_add_i32 s18, s50, s26
	global_load_lds_dwordx4 v[140:141], off
	v_lshl_add_u64 v[140:141], s[14:15], 0, v[0:1]
	s_mov_b32 m0, s18
	s_nop 0
	global_load_lds_dwordx4 v[140:141], off
	v_lshl_add_u64 v[140:141], s[14:15], 0, v[130:131]
	s_add_i32 m0, s18, 0x2000
	s_nop 0
	global_load_lds_dwordx4 v[140:141], off
	v_lshl_add_u64 v[140:141], v[188:189], 0, s[34:35]
	s_mov_b32 m0, s39
	s_nop 0
	global_load_lds_dwordx4 v[140:141], off
	v_lshl_add_u64 v[140:141], v[210:211], 0, s[34:35]
	s_mov_b32 m0, s40
	s_nop 0
	global_load_lds_dwordx4 v[140:141], off
	s_waitcnt vmcnt(8)
	s_waitcnt lgkmcnt(0)
	s_setprio 1
	s_barrier
	v_mfma_f32_16x16x32_bf16 v[62:65], v[146:149], v[190:193], v[62:65]
	v_mfma_f32_16x16x32_bf16 v[62:65], v[150:153], v[194:197], v[62:65]
	v_mfma_f32_16x16x32_bf16 v[54:57], v[150:153], v[202:205], v[54:57]
	v_mfma_f32_16x16x32_bf16 v[54:57], v[146:149], v[198:201], v[54:57]
	v_mfma_f32_16x16x32_bf16 v[38:41], v[146:149], v[206:209], v[38:41]
	v_mfma_f32_16x16x32_bf16 v[38:41], v[150:153], v[228:231], v[38:41]
	v_mfma_f32_16x16x32_bf16 v[22:25], v[150:153], v[236:239], v[22:25]
	v_mfma_f32_16x16x32_bf16 v[22:25], v[146:149], v[232:235], v[22:25]
	v_mfma_f32_16x16x32_bf16 v[14:17], v[154:157], v[232:235], v[14:17]
	v_mfma_f32_16x16x32_bf16 v[14:17], v[158:161], v[236:239], v[14:17]
	v_mfma_f32_16x16x32_bf16 v[30:33], v[158:161], v[228:231], v[30:33]
	v_mfma_f32_16x16x32_bf16 v[30:33], v[154:157], v[206:209], v[30:33]
	v_mfma_f32_16x16x32_bf16 v[46:49], v[154:157], v[198:201], v[46:49]
	v_mfma_f32_16x16x32_bf16 v[46:49], v[158:161], v[202:205], v[46:49]
	v_mfma_f32_16x16x32_bf16 v[58:61], v[158:161], v[194:197], v[58:61]
	v_mfma_f32_16x16x32_bf16 v[58:61], v[154:157], v[190:193], v[58:61]
	v_mfma_f32_16x16x32_bf16 v[50:53], v[162:165], v[190:193], v[50:53]
	v_mfma_f32_16x16x32_bf16 v[50:53], v[166:169], v[194:197], v[50:53]
	v_mfma_f32_16x16x32_bf16 v[34:37], v[166:169], v[202:205], v[34:37]
	v_mfma_f32_16x16x32_bf16 v[34:37], v[162:165], v[198:201], v[34:37]
	v_mfma_f32_16x16x32_bf16 v[18:21], v[162:165], v[206:209], v[18:21]
	v_mfma_f32_16x16x32_bf16 v[18:21], v[166:169], v[228:231], v[18:21]
	v_mfma_f32_16x16x32_bf16 v[6:9], v[166:169], v[236:239], v[6:9]
	v_mfma_f32_16x16x32_bf16 v[6:9], v[162:165], v[232:235], v[6:9]
	v_mfma_f32_16x16x32_bf16 v[2:5], v[170:173], v[232:235], v[2:5]
	v_mfma_f32_16x16x32_bf16 v[2:5], v[178:181], v[236:239], v[2:5]
	v_mfma_f32_16x16x32_bf16 v[10:13], v[178:181], v[228:231], v[10:13]
	v_mfma_f32_16x16x32_bf16 v[10:13], v[170:173], v[206:209], v[10:13]
	v_mfma_f32_16x16x32_bf16 v[26:29], v[170:173], v[198:201], v[26:29]
	v_mfma_f32_16x16x32_bf16 v[26:29], v[178:181], v[202:205], v[26:29]
	v_mfma_f32_16x16x32_bf16 v[42:45], v[178:181], v[194:197], v[42:45]
	v_mfma_f32_16x16x32_bf16 v[42:45], v[170:173], v[190:193], v[42:45]
	s_barrier
	s_setprio 0
	s_add_i32 s48, s48, 2
	s_add_u32 s46, s46, 0x100
	s_addc_u32 s47, s47, 0
	s_cmpk_gt_u32 s48, 0xa9
	s_mov_b64 s[14:15], s[16:17]
	s_cbranch_scc0 .LBB0_805
	s_and_b64 vcc, exec, s[6:7]
	s_cbranch_vccz .LBB0_808
	s_barrier
